# grid barrier leader poll: 16 per-XCC counter loads issued back-to-back with immediate offsets from s[52:53] and one wait (as the entry barrier copy does) instead of 16 serial load-wait-add steps, 9 in
# speedup vs baseline: 1.0038x; 1.0038x over previous
; __device__ __forceinline__ unsigned xb_ld(unsigned* p)              { return __hip_atomic_load(p, __ATOMIC_RELAXED, __HIP_MEMORY_SCOPE_AGENT); }
; __device__ __forceinline__ void xcd_barrier_complete(unsigned* bar, unsigned x, unsigned& nloc, unsigned& nx) {
;     const unsigned G = gridDim.x * gridDim.y * gridDim.z;
;     unsigned sum, cnt, mine, sp = 0u;
;     for (;;) {
;         sum = 0u; cnt = 0u; mine = 0u;
; #pragma unroll
;         for (unsigned j = 0; j < 16; ++j) { const unsigned c = xb_ld(&bar[XB_XCNT(j)]); sum += c; cnt += (c > 0u) ? 1u : 0u; mine = (j == x) ? c : mine; }
;         if (sum == G) break;
;         __builtin_amdgcn_s_sleep(1);
;         if ((++sp & 255u) == 0u) { if (xb_ld(&bar[XB_TMO])) break; if (sp > XB_SPIN_CAP) { atomicAdd(&bar[XB_TMO], 1u); break; } }
;     }
;     nloc = mine > 0u ? mine : 1u; nx = cnt > 0u ? cnt : 1u;
; }
.LBB0_483:
	v_readlane_b32 s2, v254, 14
	v_readlane_b32 s3, v254, 15
	global_load_dword v0, v1, s[52:53] sc1
	s_mov_b64 s[6:7], -1
	s_mov_b64 s[8:9], -1
	s_waitcnt lgkmcnt(0)
	global_load_dword v2, v1, s[52:53] offset:256 sc1
	global_load_dword v3, v1, s[52:53] offset:512 sc1
	global_load_dword v4, v1, s[52:53] offset:768 sc1
	global_load_dword v5, v1, s[52:53] offset:1024 sc1
	global_load_dword v6, v1, s[52:53] offset:1280 sc1
	global_load_dword v7, v1, s[52:53] offset:1536 sc1
	global_load_dword v8, v1, s[52:53] offset:1792 sc1
	global_load_dword v9, v1, s[52:53] offset:2048 sc1
	global_load_dword v10, v1, s[52:53] offset:2304 sc1
	global_load_dword v11, v1, s[52:53] offset:2560 sc1
	global_load_dword v12, v1, s[52:53] offset:2816 sc1
	global_load_dword v13, v1, s[52:53] offset:3072 sc1
	global_load_dword v14, v1, s[52:53] offset:3328 sc1
	global_load_dword v15, v1, s[52:53] offset:3584 sc1
	global_load_dword v16, v1, s[52:53] offset:3840 sc1
	s_waitcnt vmcnt(0)
	v_add_u32_e32 v17, v2, v0
	v_add_u32_e32 v17, v17, v3
	v_add_u32_e32 v17, v17, v4
	v_add_u32_e32 v17, v17, v5
	v_add_u32_e32 v17, v17, v6
	v_add_u32_e32 v17, v17, v7
	v_add_u32_e32 v17, v17, v8
	v_add_u32_e32 v17, v17, v9
	v_add_u32_e32 v17, v17, v10
	v_add_u32_e32 v17, v17, v11
	v_add_u32_e32 v17, v17, v12
	v_add_u32_e32 v17, v17, v13
	v_add_u32_e32 v17, v17, v14
	v_add_u32_e32 v17, v17, v15
	v_add_u32_e32 v17, v17, v16
	v_cmp_eq_u32_e32 vcc, s47, v17
	s_cbranch_vccnz .LBB0_482
	s_and_b32 s6, s13, 0xff
	s_cmp_eq_u32 s6, 0
	s_mov_b64 s[6:7], -1
	s_mov_b64 s[10:11], -1
	s_sleep 1
	s_cbranch_scc1 .LBB0_487
	s_and_b64 vcc, exec, s[10:11]
	s_cbranch_vccz .LBB0_482

; __device__ __forceinline__ unsigned xb_ld(unsigned* p)              { return __hip_atomic_load(p, __ATOMIC_RELAXED, __HIP_MEMORY_SCOPE_AGENT); }
; __device__ __forceinline__ void xcd_barrier_complete(unsigned* bar, unsigned x, unsigned& nloc, unsigned& nx) {
;     const unsigned G = gridDim.x * gridDim.y * gridDim.z;
;     unsigned sum, cnt, mine, sp = 0u;
;     for (;;) {
;         sum = 0u; cnt = 0u; mine = 0u;
; #pragma unroll
;         for (unsigned j = 0; j < 16; ++j) { const unsigned c = xb_ld(&bar[XB_XCNT(j)]); sum += c; cnt += (c > 0u) ? 1u : 0u; mine = (j == x) ? c : mine; }
;         if (sum == G) break;
;         __builtin_amdgcn_s_sleep(1);
;         if ((++sp & 255u) == 0u) { if (xb_ld(&bar[XB_TMO])) break; if (sp > XB_SPIN_CAP) { atomicAdd(&bar[XB_TMO], 1u); break; } }
;     }
;     nloc = mine > 0u ? mine : 1u; nx = cnt > 0u ? cnt : 1u;
; }
.LBB0_642:
	v_readlane_b32 s4, v254, 14
	v_readlane_b32 s5, v254, 15
	global_load_dword v0, v1, s[52:53] sc1
	s_mov_b64 s[6:7], -1
	s_mov_b64 s[8:9], -1
	s_waitcnt lgkmcnt(0)
	global_load_dword v2, v1, s[52:53] offset:256 sc1
	global_load_dword v3, v1, s[52:53] offset:512 sc1
	global_load_dword v4, v1, s[52:53] offset:768 sc1
	global_load_dword v5, v1, s[52:53] offset:1024 sc1
	global_load_dword v6, v1, s[52:53] offset:1280 sc1
	global_load_dword v7, v1, s[52:53] offset:1536 sc1
	global_load_dword v8, v1, s[52:53] offset:1792 sc1
	global_load_dword v9, v1, s[52:53] offset:2048 sc1
	global_load_dword v10, v1, s[52:53] offset:2304 sc1
	global_load_dword v11, v1, s[52:53] offset:2560 sc1
	global_load_dword v12, v1, s[52:53] offset:2816 sc1
	global_load_dword v13, v1, s[52:53] offset:3072 sc1
	global_load_dword v14, v1, s[52:53] offset:3328 sc1
	global_load_dword v15, v1, s[52:53] offset:3584 sc1
	global_load_dword v16, v1, s[52:53] offset:3840 sc1
	s_waitcnt vmcnt(0)
	v_add_u32_e32 v17, v2, v0
	v_add_u32_e32 v17, v17, v3
	v_add_u32_e32 v17, v17, v4
	v_add_u32_e32 v17, v17, v5
	v_add_u32_e32 v17, v17, v6
	v_add_u32_e32 v17, v17, v7
	v_add_u32_e32 v17, v17, v8
	v_add_u32_e32 v17, v17, v9
	v_add_u32_e32 v17, v17, v10
	v_add_u32_e32 v17, v17, v11
	v_add_u32_e32 v17, v17, v12
	v_add_u32_e32 v17, v17, v13
	v_add_u32_e32 v17, v17, v14
	v_add_u32_e32 v17, v17, v15
	v_add_u32_e32 v17, v17, v16
	v_cmp_eq_u32_e32 vcc, s47, v17
	s_cbranch_vccnz .LBB0_641
	s_and_b32 s6, s13, 0xff
	s_cmp_eq_u32 s6, 0
	s_mov_b64 s[6:7], -1
	s_mov_b64 s[10:11], -1
	s_sleep 1
	s_cbranch_scc1 .LBB0_646
	s_and_b64 vcc, exec, s[10:11]
	s_cbranch_vccz .LBB0_641

; __device__ __forceinline__ unsigned xb_ld(unsigned* p)              { return __hip_atomic_load(p, __ATOMIC_RELAXED, __HIP_MEMORY_SCOPE_AGENT); }
; __device__ __forceinline__ void xcd_barrier_complete(unsigned* bar, unsigned x, unsigned& nloc, unsigned& nx) {
;     const unsigned G = gridDim.x * gridDim.y * gridDim.z;
;     unsigned sum, cnt, mine, sp = 0u;
;     for (;;) {
;         sum = 0u; cnt = 0u; mine = 0u;
; #pragma unroll
;         for (unsigned j = 0; j < 16; ++j) { const unsigned c = xb_ld(&bar[XB_XCNT(j)]); sum += c; cnt += (c > 0u) ? 1u : 0u; mine = (j == x) ? c : mine; }
;         if (sum == G) break;
;         __builtin_amdgcn_s_sleep(1);
;         if ((++sp & 255u) == 0u) { if (xb_ld(&bar[XB_TMO])) break; if (sp > XB_SPIN_CAP) { atomicAdd(&bar[XB_TMO], 1u); break; } }
;     }
;     nloc = mine > 0u ? mine : 1u; nx = cnt > 0u ? cnt : 1u;
; }
.LBB0_1180:
	v_readlane_b32 s2, v254, 14
	v_readlane_b32 s3, v254, 15
	global_load_dword v0, v1, s[52:53] sc1
	s_mov_b64 s[6:7], -1
	s_mov_b64 s[12:13], -1
	s_waitcnt lgkmcnt(0)
	global_load_dword v2, v1, s[52:53] offset:256 sc1
	global_load_dword v3, v1, s[52:53] offset:512 sc1
	global_load_dword v4, v1, s[52:53] offset:768 sc1
	global_load_dword v5, v1, s[52:53] offset:1024 sc1
	global_load_dword v6, v1, s[52:53] offset:1280 sc1
	global_load_dword v7, v1, s[52:53] offset:1536 sc1
	global_load_dword v8, v1, s[52:53] offset:1792 sc1
	global_load_dword v9, v1, s[52:53] offset:2048 sc1
	global_load_dword v10, v1, s[52:53] offset:2304 sc1
	global_load_dword v11, v1, s[52:53] offset:2560 sc1
	global_load_dword v12, v1, s[52:53] offset:2816 sc1
	global_load_dword v13, v1, s[52:53] offset:3072 sc1
	global_load_dword v14, v1, s[52:53] offset:3328 sc1
	global_load_dword v15, v1, s[52:53] offset:3584 sc1
	global_load_dword v16, v1, s[52:53] offset:3840 sc1
	s_waitcnt vmcnt(0)
	v_add_u32_e32 v17, v2, v0
	v_add_u32_e32 v17, v17, v3
	v_add_u32_e32 v17, v17, v4
	v_add_u32_e32 v17, v17, v5
	v_add_u32_e32 v17, v17, v6
	v_add_u32_e32 v17, v17, v7
	v_add_u32_e32 v17, v17, v8
	v_add_u32_e32 v17, v17, v9
	v_add_u32_e32 v17, v17, v10
	v_add_u32_e32 v17, v17, v11
	v_add_u32_e32 v17, v17, v12
	v_add_u32_e32 v17, v17, v13
	v_add_u32_e32 v17, v17, v14
	v_add_u32_e32 v17, v17, v15
	v_add_u32_e32 v17, v17, v16
	v_cmp_eq_u32_e32 vcc, s47, v17
	s_cbranch_vccnz .LBB0_1179
	s_and_b32 s6, s19, 0xff
	s_cmp_eq_u32 s6, 0
	s_mov_b64 s[6:7], -1
	s_mov_b64 s[16:17], -1
	s_sleep 1
	s_cbranch_scc1 .LBB0_1184
	s_and_b64 vcc, exec, s[16:17]
	s_cbranch_vccz .LBB0_1179

; __device__ __forceinline__ unsigned xb_ld(unsigned* p)              { return __hip_atomic_load(p, __ATOMIC_RELAXED, __HIP_MEMORY_SCOPE_AGENT); }
; __device__ __forceinline__ void xcd_barrier_complete(unsigned* bar, unsigned x, unsigned& nloc, unsigned& nx) {
;     const unsigned G = gridDim.x * gridDim.y * gridDim.z;
;     unsigned sum, cnt, mine, sp = 0u;
;     for (;;) {
;         sum = 0u; cnt = 0u; mine = 0u;
; #pragma unroll
;         for (unsigned j = 0; j < 16; ++j) { const unsigned c = xb_ld(&bar[XB_XCNT(j)]); sum += c; cnt += (c > 0u) ? 1u : 0u; mine = (j == x) ? c : mine; }
;         if (sum == G) break;
;         __builtin_amdgcn_s_sleep(1);
;         if ((++sp & 255u) == 0u) { if (xb_ld(&bar[XB_TMO])) break; if (sp > XB_SPIN_CAP) { atomicAdd(&bar[XB_TMO], 1u); break; } }
;     }
;     nloc = mine > 0u ? mine : 1u; nx = cnt > 0u ? cnt : 1u;
; }
.LBB0_1283:
	v_readlane_b32 s2, v254, 14
	v_readlane_b32 s3, v254, 15
	global_load_dword v0, v1, s[52:53] sc1
	s_mov_b64 s[14:15], -1
	s_mov_b64 s[16:17], -1
	s_waitcnt lgkmcnt(0)
	global_load_dword v2, v1, s[52:53] offset:256 sc1
	global_load_dword v3, v1, s[52:53] offset:512 sc1
	global_load_dword v4, v1, s[52:53] offset:768 sc1
	global_load_dword v5, v1, s[52:53] offset:1024 sc1
	global_load_dword v6, v1, s[52:53] offset:1280 sc1
	global_load_dword v7, v1, s[52:53] offset:1536 sc1
	global_load_dword v8, v1, s[52:53] offset:1792 sc1
	global_load_dword v9, v1, s[52:53] offset:2048 sc1
	global_load_dword v10, v1, s[52:53] offset:2304 sc1
	global_load_dword v11, v1, s[52:53] offset:2560 sc1
	global_load_dword v12, v1, s[52:53] offset:2816 sc1
	global_load_dword v13, v1, s[52:53] offset:3072 sc1
	global_load_dword v14, v1, s[52:53] offset:3328 sc1
	global_load_dword v15, v1, s[52:53] offset:3584 sc1
	global_load_dword v16, v1, s[52:53] offset:3840 sc1
	s_waitcnt vmcnt(0)
	v_add_u32_e32 v17, v2, v0
	v_add_u32_e32 v17, v17, v3
	v_add_u32_e32 v17, v17, v4
	v_add_u32_e32 v17, v17, v5
	v_add_u32_e32 v17, v17, v6
	v_add_u32_e32 v17, v17, v7
	v_add_u32_e32 v17, v17, v8
	v_add_u32_e32 v17, v17, v9
	v_add_u32_e32 v17, v17, v10
	v_add_u32_e32 v17, v17, v11
	v_add_u32_e32 v17, v17, v12
	v_add_u32_e32 v17, v17, v13
	v_add_u32_e32 v17, v17, v14
	v_add_u32_e32 v17, v17, v15
	v_add_u32_e32 v17, v17, v16
	v_cmp_eq_u32_e32 vcc, s47, v17
	s_cbranch_vccnz .LBB0_1282
	s_and_b32 s14, s21, 0xff
	s_cmp_eq_u32 s14, 0
	s_mov_b64 s[14:15], -1
	s_mov_b64 s[18:19], -1
	s_sleep 1
	s_cbranch_scc1 .LBB0_1287
	s_and_b64 vcc, exec, s[18:19]
	s_cbranch_vccz .LBB0_1282

; __device__ __forceinline__ unsigned xb_ld(unsigned* p)              { return __hip_atomic_load(p, __ATOMIC_RELAXED, __HIP_MEMORY_SCOPE_AGENT); }
; __device__ __forceinline__ void xcd_barrier_complete(unsigned* bar, unsigned x, unsigned& nloc, unsigned& nx) {
;     const unsigned G = gridDim.x * gridDim.y * gridDim.z;
;     unsigned sum, cnt, mine, sp = 0u;
;     for (;;) {
;         sum = 0u; cnt = 0u; mine = 0u;
; #pragma unroll
;         for (unsigned j = 0; j < 16; ++j) { const unsigned c = xb_ld(&bar[XB_XCNT(j)]); sum += c; cnt += (c > 0u) ? 1u : 0u; mine = (j == x) ? c : mine; }
;         if (sum == G) break;
;         __builtin_amdgcn_s_sleep(1);
;         if ((++sp & 255u) == 0u) { if (xb_ld(&bar[XB_TMO])) break; if (sp > XB_SPIN_CAP) { atomicAdd(&bar[XB_TMO], 1u); break; } }
;     }
;     nloc = mine > 0u ? mine : 1u; nx = cnt > 0u ? cnt : 1u;
; }
.LBB0_1351:
	v_readlane_b32 s2, v254, 14
	v_readlane_b32 s3, v254, 15
	global_load_dword v0, v1, s[52:53] sc1
	s_mov_b64 s[16:17], -1
	s_mov_b64 s[18:19], -1
	s_waitcnt lgkmcnt(0)
	global_load_dword v2, v1, s[52:53] offset:256 sc1
	global_load_dword v3, v1, s[52:53] offset:512 sc1
	global_load_dword v4, v1, s[52:53] offset:768 sc1
	global_load_dword v5, v1, s[52:53] offset:1024 sc1
	global_load_dword v6, v1, s[52:53] offset:1280 sc1
	global_load_dword v7, v1, s[52:53] offset:1536 sc1
	global_load_dword v8, v1, s[52:53] offset:1792 sc1
	global_load_dword v9, v1, s[52:53] offset:2048 sc1
	global_load_dword v10, v1, s[52:53] offset:2304 sc1
	global_load_dword v11, v1, s[52:53] offset:2560 sc1
	global_load_dword v12, v1, s[52:53] offset:2816 sc1
	global_load_dword v13, v1, s[52:53] offset:3072 sc1
	global_load_dword v14, v1, s[52:53] offset:3328 sc1
	global_load_dword v15, v1, s[52:53] offset:3584 sc1
	global_load_dword v16, v1, s[52:53] offset:3840 sc1
	s_waitcnt vmcnt(0)
	v_add_u32_e32 v17, v2, v0
	v_add_u32_e32 v17, v17, v3
	v_add_u32_e32 v17, v17, v4
	v_add_u32_e32 v17, v17, v5
	v_add_u32_e32 v17, v17, v6
	v_add_u32_e32 v17, v17, v7
	v_add_u32_e32 v17, v17, v8
	v_add_u32_e32 v17, v17, v9
	v_add_u32_e32 v17, v17, v10
	v_add_u32_e32 v17, v17, v11
	v_add_u32_e32 v17, v17, v12
	v_add_u32_e32 v17, v17, v13
	v_add_u32_e32 v17, v17, v14
	v_add_u32_e32 v17, v17, v15
	v_add_u32_e32 v17, v17, v16
	v_cmp_eq_u32_e32 vcc, s47, v17
	s_cbranch_vccnz .LBB0_1350
	s_and_b32 s16, s23, 0xff
	s_cmp_eq_u32 s16, 0
	s_mov_b64 s[16:17], -1
	s_mov_b64 s[20:21], -1
	s_sleep 1
	s_cbranch_scc1 .LBB0_1355
	s_and_b64 vcc, exec, s[20:21]
	s_cbranch_vccz .LBB0_1350

; __device__ __forceinline__ unsigned xb_ld(unsigned* p)              { return __hip_atomic_load(p, __ATOMIC_RELAXED, __HIP_MEMORY_SCOPE_AGENT); }
; __device__ __forceinline__ void xcd_barrier_complete(unsigned* bar, unsigned x, unsigned& nloc, unsigned& nx) {
;     const unsigned G = gridDim.x * gridDim.y * gridDim.z;
;     unsigned sum, cnt, mine, sp = 0u;
;     for (;;) {
;         sum = 0u; cnt = 0u; mine = 0u;
; #pragma unroll
;         for (unsigned j = 0; j < 16; ++j) { const unsigned c = xb_ld(&bar[XB_XCNT(j)]); sum += c; cnt += (c > 0u) ? 1u : 0u; mine = (j == x) ? c : mine; }
;         if (sum == G) break;
;         __builtin_amdgcn_s_sleep(1);
;         if ((++sp & 255u) == 0u) { if (xb_ld(&bar[XB_TMO])) break; if (sp > XB_SPIN_CAP) { atomicAdd(&bar[XB_TMO], 1u); break; } }
;     }
;     nloc = mine > 0u ? mine : 1u; nx = cnt > 0u ? cnt : 1u;
; }
.LBB0_1722:
	v_readlane_b32 s2, v254, 14
	v_readlane_b32 s3, v254, 15
	global_load_dword v0, v1, s[52:53] sc1
	s_mov_b64 s[8:9], -1
	s_mov_b64 s[10:11], -1
	s_waitcnt lgkmcnt(0)
	global_load_dword v2, v1, s[52:53] offset:256 sc1
	global_load_dword v3, v1, s[52:53] offset:512 sc1
	global_load_dword v4, v1, s[52:53] offset:768 sc1
	global_load_dword v5, v1, s[52:53] offset:1024 sc1
	global_load_dword v6, v1, s[52:53] offset:1280 sc1
	global_load_dword v7, v1, s[52:53] offset:1536 sc1
	global_load_dword v8, v1, s[52:53] offset:1792 sc1
	global_load_dword v9, v1, s[52:53] offset:2048 sc1
	global_load_dword v10, v1, s[52:53] offset:2304 sc1
	global_load_dword v11, v1, s[52:53] offset:2560 sc1
	global_load_dword v12, v1, s[52:53] offset:2816 sc1
	global_load_dword v13, v1, s[52:53] offset:3072 sc1
	global_load_dword v14, v1, s[52:53] offset:3328 sc1
	global_load_dword v15, v1, s[52:53] offset:3584 sc1
	global_load_dword v16, v1, s[52:53] offset:3840 sc1
	s_waitcnt vmcnt(0)
	v_add_u32_e32 v17, v2, v0
	v_add_u32_e32 v17, v17, v3
	v_add_u32_e32 v17, v17, v4
	v_add_u32_e32 v17, v17, v5
	v_add_u32_e32 v17, v17, v6
	v_add_u32_e32 v17, v17, v7
	v_add_u32_e32 v17, v17, v8
	v_add_u32_e32 v17, v17, v9
	v_add_u32_e32 v17, v17, v10
	v_add_u32_e32 v17, v17, v11
	v_add_u32_e32 v17, v17, v12
	v_add_u32_e32 v17, v17, v13
	v_add_u32_e32 v17, v17, v14
	v_add_u32_e32 v17, v17, v15
	v_add_u32_e32 v17, v17, v16
	v_cmp_eq_u32_e32 vcc, s47, v17
	s_cbranch_vccnz .LBB0_1721
	s_and_b32 s8, s17, 0xff
	s_cmp_eq_u32 s8, 0
	s_mov_b64 s[8:9], -1
	s_mov_b64 s[14:15], -1
	s_sleep 1
	s_cbranch_scc1 .LBB0_1726
	s_and_b64 vcc, exec, s[14:15]
	s_cbranch_vccz .LBB0_1721
